# MLA loop regenerated: next item's first softmax quarter in the tail gaps, QK chains un-interleaved, even VALU spacing, reads 5 MFMAs ahead via 8-buffer pool
# speedup vs baseline: 1.0218x; 1.0137x over previous
.LBB0_493:
	v_lshlrev_b32_e32 v34, 10, v0
	v_or_b32_e32 v1, v34, v172
	v_add_u32_e32 v0, 0, v1
	s_waitcnt vmcnt(5)
	s_waitcnt vmcnt(4)
	s_waitcnt vmcnt(3)
	s_waitcnt vmcnt(2)
	s_waitcnt vmcnt(1)
	s_waitcnt vmcnt(0)
	ds_read_b128 v[18:21], v0
	ds_read_b128 v[2:5], v0 offset:512
	s_waitcnt lgkmcnt(0)
	v_mfma_f32_32x32x16_bf16 v[2:17], v[2:5], v[118:121], 0
	ds_read_b128 v[36:39], v0 offset:2048
	ds_read_b128 v[22:25], v0 offset:2560
	s_lshl_b32 s9, s42, 8
	s_lshl_b32 s34, s3, 5
	s_lshl_b32 s10, s10, 10
	s_add_i32 s6, s34, s9
	s_lshl_b32 s11, s2, 6
	s_lshl_b32 s46, s42, 2
	s_waitcnt lgkmcnt(0)
	v_mfma_f32_32x32x16_bf16 v[2:17], v[22:25], v[114:117], v[2:17]
	ds_read_b128 v[40:43], v0 offset:4096
	ds_read_b128 v[22:25], v0 offset:4608
	s_and_b32 s45, s10, 0x7fffe000
	s_ashr_i32 s27, s6, 6
	s_and_b32 s35, s11, 0x1c0
	s_add_i32 s47, s46, 4
	s_add_i32 s45, s45, s9
	s_waitcnt lgkmcnt(0)
	v_mfma_f32_32x32x16_bf16 v[2:17], v[22:25], v[110:113], v[2:17]
	ds_read_b128 v[44:47], v0 offset:6144
	ds_read_b128 v[22:25], v0 offset:6656
	s_waitcnt lgkmcnt(0)
	v_mfma_f32_32x32x16_bf16 v[2:17], v[22:25], v[106:109], v[2:17]
	ds_read_b128 v[48:51], v0 offset:8192
	ds_read_b128 v[22:25], v0 offset:8704
	s_waitcnt lgkmcnt(0)
	v_mfma_f32_32x32x16_bf16 v[2:17], v[22:25], v[102:105], v[2:17]
	ds_read_b128 v[52:55], v0 offset:10240
	ds_read_b128 v[22:25], v0 offset:10752
	s_waitcnt lgkmcnt(0)
	v_mfma_f32_32x32x16_bf16 v[2:17], v[22:25], v[98:101], v[2:17]
	v_mfma_f32_32x32x16_bf16 v[18:33], v[18:21], v[118:121], 0
	v_mov_b32_e32 v0, v173
	s_mov_b64 s[10:11], -1
	s_cmp_lt_i32 s27, 0
	v_mfma_f32_32x32x16_bf16 v[18:33], v[36:39], v[114:117], v[18:33]
	v_mfma_f32_32x32x16_bf16 v[18:33], v[40:43], v[110:113], v[18:33]
	v_mfma_f32_32x32x16_bf16 v[18:33], v[44:47], v[106:109], v[18:33]
	v_mfma_f32_32x32x16_bf16 v[18:33], v[48:51], v[102:105], v[18:33]
	v_mfma_f32_32x32x16_bf16 v[18:33], v[52:55], v[98:101], v[18:33]
	s_cbranch_scc1 .LBB0_520
	s_cmp_lt_u32 s27, 2
	s_mov_b32 s10, 2
	s_cbranch_scc1 .LBB0_502
	v_add_u32_e32 v218, 0x1000, v170
	v_add_u32_e32 v219, 0x2000, v170
	s_lshl_b32 s9, s3, 10
	s_and_b32 s28, s9, 0xc00
	s_add_u32 s29, s18, s40
	s_addc_u32 s30, s19, s41
	s_add_u32 s31, s38, s44
	s_addc_u32 s33, s39, s43
	v_add_u32_e32 v139, v172, v34
	v_mov_b32_e32 v138, 0
	s_mov_b32 s48, 2
	s_mov_b32 s49, 4
	s_mov_b32 s50, 0
	s_mov_b32 s51, 0
	v_mov_b32_e32 v66, v0
	v_mov_b32_e32 v67, v0
	v_mov_b32_e32 v68, v0
	v_mov_b32_e32 v69, v0
	v_mov_b32_e32 v70, v0
	v_mov_b32_e32 v71, v0
	v_mov_b32_e32 v72, v0
	v_mov_b32_e32 v73, v0
	v_mov_b32_e32 v74, v0
	v_mov_b32_e32 v75, v0
	v_mov_b32_e32 v76, v0
	v_mov_b32_e32 v77, v0
	v_mov_b32_e32 v78, v0
	v_mov_b32_e32 v79, v0
	v_mov_b32_e32 v80, v0
	v_mov_b32_e32 v81, v0
	v_mov_b32_e32 v82, v0
	v_mov_b32_e32 v83, v0
	v_mov_b32_e32 v84, v0
	v_mov_b32_e32 v85, v0
	v_mov_b32_e32 v86, v0
	v_mov_b32_e32 v87, v0
	v_mov_b32_e32 v88, v0
	v_mov_b32_e32 v89, v0
	v_mov_b32_e32 v90, v0
	v_mov_b32_e32 v91, v0
	v_mov_b32_e32 v92, v0
	v_mov_b32_e32 v93, v0
	v_mov_b32_e32 v94, v0
	v_mov_b32_e32 v95, v0
	v_mov_b32_e32 v96, v0
	v_mov_b32_e32 v97, v0
	v_mov_b32_e32 v163, 0
	v_mov_b32_e32 v162, 0
	v_mov_b32_e32 v140, v139
	ds_read_b128 v[142:145], v140 offset:12288
	ds_read_b128 v[146:149], v140 offset:12800
	ds_read_b128 v[150:153], v140 offset:20480
	ds_read_b128 v[154:157], v140 offset:22528
	ds_read_b128 v[158:161], v140 offset:24576
	v_exp_f32_e32 v18, v18
	v_exp_f32_e32 v19, v19
	v_exp_f32_e32 v20, v20
	v_exp_f32_e32 v21, v21
	v_exp_f32_e32 v22, v22
	v_exp_f32_e32 v23, v23
	v_exp_f32_e32 v24, v24
	v_exp_f32_e32 v25, v25
	v_add_f32_e32 v163, v163, v18
	v_add_f32_e32 v162, v162, v19
	v_add_f32_e32 v163, v163, v20
	v_add_f32_e32 v162, v162, v21
	v_add_f32_e32 v163, v163, v22
	v_cvt_pk_bf16_f32 v134, v18, v19
	v_cvt_pk_bf16_f32 v135, v20, v21
	v_cvt_pk_bf16_f32 v136, v22, v23
	v_cvt_pk_bf16_f32 v137, v24, v25
	v_add_f32_e32 v162, v162, v23
	v_add_f32_e32 v163, v163, v24
	v_add_f32_e32 v162, v162, v25

.LBB0_500:
	s_mul_hi_u32 s9, s48, 0xaaaaaaab
	s_lshr_b32 s9, s9, 2
	s_mul_i32 s9, s9, 0xfffe2000
	s_add_i32 s52, s9, 0
	v_add_u32_e32 v141, s50, v139
	v_add_u32_e32 v220, s52, v141
	s_waitcnt lgkmcnt(4)
	v_mfma_f32_32x32x16_bf16 v[66:81], v[142:145], v[134:137], v[66:81]
	ds_read_b128 v[224:227], v140 offset:14336
	v_exp_f32_e32 v26, v26
	v_exp_f32_e32 v27, v27
	v_exp_f32_e32 v28, v28
	s_waitcnt lgkmcnt(4)
	v_mfma_f32_32x32x16_bf16 v[82:97], v[146:149], v[134:137], v[82:97]
	ds_read_b128 v[228:231], v140 offset:14848
	v_exp_f32_e32 v29, v29
	v_exp_f32_e32 v30, v30
	v_exp_f32_e32 v31, v31
	s_waitcnt lgkmcnt(4)
	v_mfma_f32_32x32x16_bf16 v[50:65], v[150:153], v[118:121], 0
	ds_read_b128 v[232:235], v140 offset:26624
	v_exp_f32_e32 v32, v32
	v_exp_f32_e32 v33, v33
	v_add_f32_e32 v163, v163, v26
	v_add_f32_e32 v162, v162, v27
	s_waitcnt lgkmcnt(4)
	v_mfma_f32_32x32x16_bf16 v[50:65], v[154:157], v[114:117], v[50:65]
	ds_read_b128 v[142:145], v140 offset:28672
	v_add_f32_e32 v163, v163, v28
	v_add_f32_e32 v162, v162, v29
	v_add_f32_e32 v163, v163, v30
	v_cvt_pk_bf16_f32 v130, v26, v27
	v_cvt_pk_bf16_f32 v131, v28, v29
	s_waitcnt lgkmcnt(4)
	v_mfma_f32_32x32x16_bf16 v[50:65], v[158:161], v[110:113], v[50:65]
	ds_read_b128 v[146:149], v140 offset:30720
	v_cvt_pk_bf16_f32 v132, v30, v31
	v_cvt_pk_bf16_f32 v133, v32, v33
	v_add_f32_e32 v162, v162, v31
	v_add_f32_e32 v163, v163, v32
	v_add_f32_e32 v162, v162, v33
	s_waitcnt lgkmcnt(4)
	v_mfma_f32_32x32x16_bf16 v[66:81], v[224:227], v[130:133], v[66:81]
	ds_read_b128 v[150:153], v140 offset:16384
	v_exp_f32_e32 v2, v2
	v_exp_f32_e32 v3, v3
	v_exp_f32_e32 v4, v4
	s_waitcnt lgkmcnt(4)
	v_mfma_f32_32x32x16_bf16 v[82:97], v[228:231], v[130:133], v[82:97]
	ds_read_b128 v[154:157], v140 offset:16896
	v_exp_f32_e32 v5, v5
	v_exp_f32_e32 v6, v6
	v_exp_f32_e32 v7, v7
	s_waitcnt lgkmcnt(4)
	v_mfma_f32_32x32x16_bf16 v[50:65], v[232:235], v[106:109], v[50:65]
	ds_read_b128 v[158:161], v140 offset:20992
	v_exp_f32_e32 v8, v8
	v_exp_f32_e32 v9, v9
	v_add_f32_e32 v163, v163, v2
	v_add_f32_e32 v162, v162, v3
	s_waitcnt lgkmcnt(4)
	v_mfma_f32_32x32x16_bf16 v[50:65], v[142:145], v[102:105], v[50:65]
	ds_read_b128 v[224:227], v140 offset:23040
	v_add_f32_e32 v163, v163, v4
	v_add_f32_e32 v162, v162, v5
	v_add_f32_e32 v163, v163, v6
	v_cvt_pk_bf16_f32 v134, v2, v3
	v_cvt_pk_bf16_f32 v135, v4, v5
	s_waitcnt lgkmcnt(4)
	v_mfma_f32_32x32x16_bf16 v[50:65], v[146:149], v[98:101], v[50:65]
	ds_read_b128 v[228:231], v140 offset:25088
	v_cvt_pk_bf16_f32 v136, v6, v7
	v_cvt_pk_bf16_f32 v137, v8, v9
	v_add_f32_e32 v162, v162, v7
	v_add_f32_e32 v163, v163, v8
	v_add_f32_e32 v162, v162, v9
	s_waitcnt lgkmcnt(4)
	v_mfma_f32_32x32x16_bf16 v[66:81], v[150:153], v[134:137], v[66:81]
	ds_read_b128 v[232:235], v140 offset:18432
	v_exp_f32_e32 v10, v10
	v_exp_f32_e32 v11, v11
	v_exp_f32_e32 v12, v12
	s_waitcnt lgkmcnt(4)
	v_mfma_f32_32x32x16_bf16 v[82:97], v[154:157], v[134:137], v[82:97]
	ds_read_b128 v[142:145], v140 offset:18944
	v_exp_f32_e32 v13, v13
	v_exp_f32_e32 v14, v14
	v_exp_f32_e32 v15, v15
	s_waitcnt lgkmcnt(4)
	v_mfma_f32_32x32x16_bf16 v[34:49], v[158:161], v[118:121], 0
	ds_read_b128 v[146:149], v140 offset:27136
	v_exp_f32_e32 v16, v16
	v_exp_f32_e32 v17, v17
	v_add_f32_e32 v163, v163, v10
	v_add_f32_e32 v162, v162, v11
	s_waitcnt lgkmcnt(4)
	v_mfma_f32_32x32x16_bf16 v[34:49], v[224:227], v[114:117], v[34:49]
	ds_read_b128 v[150:153], v140 offset:29184
	v_add_f32_e32 v163, v163, v12
	v_add_f32_e32 v162, v162, v13
	v_add_f32_e32 v163, v163, v14
	v_cvt_pk_bf16_f32 v130, v10, v11
	v_cvt_pk_bf16_f32 v131, v12, v13
	s_waitcnt lgkmcnt(4)
	v_mfma_f32_32x32x16_bf16 v[34:49], v[228:231], v[110:113], v[34:49]
	ds_read_b128 v[154:157], v140 offset:31232
	v_cvt_pk_bf16_f32 v132, v14, v15
	v_cvt_pk_bf16_f32 v133, v16, v17
	v_add_f32_e32 v162, v162, v15
	v_add_f32_e32 v163, v163, v16
	v_add_f32_e32 v162, v162, v17
	s_waitcnt lgkmcnt(4)
	v_mfma_f32_32x32x16_bf16 v[66:81], v[232:235], v[130:133], v[66:81]
	ds_read_b128 v[158:161], v140 offset:32768
	v_exp_f32_e32 v50, v50
	v_exp_f32_e32 v51, v51
	v_exp_f32_e32 v52, v52
	s_waitcnt lgkmcnt(4)
	v_mfma_f32_32x32x16_bf16 v[82:97], v[142:145], v[130:133], v[82:97]
	ds_read_b128 v[224:227], v140 offset:33280
	v_exp_f32_e32 v53, v53
	v_exp_f32_e32 v54, v54
	v_exp_f32_e32 v55, v55
	s_waitcnt lgkmcnt(4)
	v_mfma_f32_32x32x16_bf16 v[34:49], v[146:149], v[106:109], v[34:49]
	ds_read_b128 v[228:231], v220 offset:40960
	v_exp_f32_e32 v56, v56
	v_exp_f32_e32 v57, v57
	v_add_f32_e32 v163, v163, v50
	v_add_f32_e32 v162, v162, v51
	s_waitcnt lgkmcnt(4)
	v_mfma_f32_32x32x16_bf16 v[34:49], v[150:153], v[102:105], v[34:49]
	ds_read_b128 v[232:235], v220 offset:43008
	v_add_f32_e32 v163, v163, v52
	v_add_f32_e32 v162, v162, v53
	v_add_f32_e32 v163, v163, v54
	v_cvt_pk_bf16_f32 v134, v50, v51
	v_cvt_pk_bf16_f32 v135, v52, v53
	s_waitcnt lgkmcnt(4)
	v_mfma_f32_32x32x16_bf16 v[34:49], v[154:157], v[98:101], v[34:49]
	ds_read_b128 v[142:145], v220 offset:45056
	v_cvt_pk_bf16_f32 v136, v54, v55
	v_cvt_pk_bf16_f32 v137, v56, v57
	v_add_f32_e32 v162, v162, v55
	v_add_f32_e32 v163, v163, v56
	v_add_f32_e32 v162, v162, v57
	s_add_i32 s10, s51, 4
	s_cmp_le_i32 s10, s27
	s_cbranch_scc0 .Lmla_i2_last
	s_waitcnt lgkmcnt(4)
	v_mfma_f32_32x32x16_bf16 v[66:81], v[158:161], v[134:137], v[66:81]
	ds_read_b128 v[146:149], v140 offset:34816
	v_exp_f32_e32 v58, v58
	v_exp_f32_e32 v59, v59
	v_exp_f32_e32 v60, v60
	s_waitcnt lgkmcnt(4)
	v_mfma_f32_32x32x16_bf16 v[82:97], v[224:227], v[134:137], v[82:97]
	ds_read_b128 v[150:153], v140 offset:35328
	v_exp_f32_e32 v61, v61
	v_exp_f32_e32 v62, v62
	v_exp_f32_e32 v63, v63
	s_waitcnt lgkmcnt(4)
	v_mfma_f32_32x32x16_bf16 v[18:33], v[228:231], v[118:121], 0
	ds_read_b128 v[154:157], v220 offset:47104
	v_exp_f32_e32 v64, v64
	v_exp_f32_e32 v65, v65
	v_add_f32_e32 v163, v163, v58
	v_add_f32_e32 v162, v162, v59
	s_waitcnt lgkmcnt(4)
	v_mfma_f32_32x32x16_bf16 v[18:33], v[232:235], v[114:117], v[18:33]
	ds_read_b128 v[158:161], v220 offset:49152
	v_add_f32_e32 v163, v163, v60
	v_add_f32_e32 v162, v162, v61
	v_add_f32_e32 v163, v163, v62
	v_cvt_pk_bf16_f32 v130, v58, v59
	v_cvt_pk_bf16_f32 v131, v60, v61
	s_waitcnt lgkmcnt(4)
	v_mfma_f32_32x32x16_bf16 v[18:33], v[142:145], v[110:113], v[18:33]
	ds_read_b128 v[224:227], v220 offset:51200
	v_cvt_pk_bf16_f32 v132, v62, v63
	v_cvt_pk_bf16_f32 v133, v64, v65
	v_add_f32_e32 v162, v162, v63
	v_add_f32_e32 v163, v163, v64
	v_add_f32_e32 v162, v162, v65
	s_waitcnt lgkmcnt(4)
	v_mfma_f32_32x32x16_bf16 v[66:81], v[146:149], v[130:133], v[66:81]
	ds_read_b128 v[228:231], v140 offset:36864
	v_exp_f32_e32 v34, v34
	v_exp_f32_e32 v35, v35
	v_exp_f32_e32 v36, v36
	s_waitcnt lgkmcnt(4)
	v_mfma_f32_32x32x16_bf16 v[82:97], v[150:153], v[130:133], v[82:97]
	ds_read_b128 v[232:235], v140 offset:37376
	v_exp_f32_e32 v37, v37
	v_exp_f32_e32 v38, v38
	v_exp_f32_e32 v39, v39
	s_waitcnt lgkmcnt(4)
	v_mfma_f32_32x32x16_bf16 v[18:33], v[154:157], v[106:109], v[18:33]
	ds_read_b128 v[142:145], v220 offset:41472
	v_exp_f32_e32 v40, v40
	v_exp_f32_e32 v41, v41
	v_add_f32_e32 v163, v163, v34
	v_add_f32_e32 v162, v162, v35
	s_waitcnt lgkmcnt(4)
	v_mfma_f32_32x32x16_bf16 v[18:33], v[158:161], v[102:105], v[18:33]
	ds_read_b128 v[146:149], v220 offset:43520
	v_add_f32_e32 v163, v163, v36
	v_add_f32_e32 v162, v162, v37
	v_add_f32_e32 v163, v163, v38
	v_cvt_pk_bf16_f32 v134, v34, v35
	v_cvt_pk_bf16_f32 v135, v36, v37
	s_waitcnt lgkmcnt(4)
	v_mfma_f32_32x32x16_bf16 v[18:33], v[224:227], v[98:101], v[18:33]
	ds_read_b128 v[150:153], v220 offset:45568
	v_cvt_pk_bf16_f32 v136, v38, v39
	v_cvt_pk_bf16_f32 v137, v40, v41
	v_add_f32_e32 v162, v162, v39
	v_add_f32_e32 v163, v163, v40
	v_add_f32_e32 v162, v162, v41
	s_waitcnt lgkmcnt(4)
	v_mfma_f32_32x32x16_bf16 v[66:81], v[228:231], v[134:137], v[66:81]
	ds_read_b128 v[154:157], v140 offset:38912
	v_exp_f32_e32 v42, v42
	v_exp_f32_e32 v43, v43
	v_exp_f32_e32 v44, v44
	s_waitcnt lgkmcnt(4)
	v_mfma_f32_32x32x16_bf16 v[82:97], v[232:235], v[134:137], v[82:97]
	ds_read_b128 v[158:161], v140 offset:39424
	v_exp_f32_e32 v45, v45
	v_exp_f32_e32 v46, v46
	v_exp_f32_e32 v47, v47
	s_waitcnt lgkmcnt(4)
	v_mfma_f32_32x32x16_bf16 v[2:17], v[142:145], v[118:121], 0
	ds_read_b128 v[224:227], v220 offset:47616
	v_exp_f32_e32 v48, v48
	v_exp_f32_e32 v49, v49
	v_add_f32_e32 v163, v163, v42
	v_add_f32_e32 v162, v162, v43
	s_waitcnt lgkmcnt(4)
	v_mfma_f32_32x32x16_bf16 v[2:17], v[146:149], v[114:117], v[2:17]
	ds_read_b128 v[228:231], v220 offset:49664
	v_add_f32_e32 v163, v163, v44
	v_add_f32_e32 v162, v162, v45
	v_add_f32_e32 v163, v163, v46
	v_cvt_pk_bf16_f32 v130, v42, v43
	v_cvt_pk_bf16_f32 v131, v44, v45
	s_waitcnt lgkmcnt(4)
	v_mfma_f32_32x32x16_bf16 v[2:17], v[150:153], v[110:113], v[2:17]
	ds_read_b128 v[232:235], v220 offset:51712
	v_cvt_pk_bf16_f32 v132, v46, v47
	v_cvt_pk_bf16_f32 v133, v48, v49
	v_add_f32_e32 v162, v162, v47
	v_add_f32_e32 v163, v163, v48
	v_add_f32_e32 v162, v162, v49
	s_waitcnt lgkmcnt(4)
	v_mfma_f32_32x32x16_bf16 v[66:81], v[154:157], v[130:133], v[66:81]
	v_add_u32_e32 v140, 0xa000, v220
	ds_read_b128 v[142:145], v140 offset:12288
	v_exp_f32_e32 v18, v18
	v_exp_f32_e32 v19, v19
	v_exp_f32_e32 v20, v20
	s_waitcnt lgkmcnt(4)
	v_mfma_f32_32x32x16_bf16 v[82:97], v[158:161], v[130:133], v[82:97]
	ds_read_b128 v[146:149], v140 offset:12800
	v_exp_f32_e32 v21, v21
	v_exp_f32_e32 v22, v22
	v_exp_f32_e32 v23, v23
	s_waitcnt lgkmcnt(4)
	v_mfma_f32_32x32x16_bf16 v[2:17], v[224:227], v[106:109], v[2:17]
	ds_read_b128 v[150:153], v140 offset:20480
	v_exp_f32_e32 v24, v24
	v_exp_f32_e32 v25, v25
	v_add_f32_e32 v163, v163, v18
	v_add_f32_e32 v162, v162, v19
	s_waitcnt lgkmcnt(4)
	v_mfma_f32_32x32x16_bf16 v[2:17], v[228:231], v[102:105], v[2:17]
	ds_read_b128 v[154:157], v140 offset:22528
	v_add_f32_e32 v163, v163, v20
	v_add_f32_e32 v162, v162, v21
	v_add_f32_e32 v163, v163, v22
	v_cvt_pk_bf16_f32 v134, v18, v19
	v_cvt_pk_bf16_f32 v135, v20, v21
	s_waitcnt lgkmcnt(4)
	v_mfma_f32_32x32x16_bf16 v[2:17], v[232:235], v[98:101], v[2:17]
	ds_read_b128 v[158:161], v140 offset:24576
	v_cvt_pk_bf16_f32 v136, v22, v23
	v_cvt_pk_bf16_f32 v137, v24, v25
	v_add_f32_e32 v162, v162, v23
	v_add_f32_e32 v163, v163, v24
	v_add_f32_e32 v162, v162, v25
	s_add_i32 s48, s48, 2
	s_add_i32 s9, s51, 2
	s_add_u32 s29, s29, 0x4000
	s_addc_u32 s30, s30, 0
	s_add_u32 s31, s31, 0x6000
	s_addc_u32 s33, s33, 0
	s_add_i32 s49, s49, 2
	s_add_i32 s50, s50, 0xa000
	s_mov_b32 s51, s9
	s_branch .LBB0_496
.Lmla_i2_last:
	s_waitcnt lgkmcnt(4)
	v_mfma_f32_32x32x16_bf16 v[66:81], v[158:161], v[134:137], v[66:81]
	ds_read_b128 v[146:149], v140 offset:34816
	v_exp_f32_e32 v58, v58
	v_exp_f32_e32 v59, v59
	v_exp_f32_e32 v60, v60
	s_waitcnt lgkmcnt(4)
	v_mfma_f32_32x32x16_bf16 v[82:97], v[224:227], v[134:137], v[82:97]
	ds_read_b128 v[150:153], v140 offset:35328
	v_exp_f32_e32 v61, v61
	v_exp_f32_e32 v62, v62
	v_exp_f32_e32 v63, v63
	s_waitcnt lgkmcnt(4)
	v_mfma_f32_32x32x16_bf16 v[18:33], v[228:231], v[118:121], 0
	ds_read_b128 v[154:157], v220 offset:47104
	v_exp_f32_e32 v64, v64
	v_exp_f32_e32 v65, v65
	v_add_f32_e32 v163, v163, v58
	v_add_f32_e32 v162, v162, v59
	s_waitcnt lgkmcnt(4)
	v_mfma_f32_32x32x16_bf16 v[18:33], v[232:235], v[114:117], v[18:33]
	ds_read_b128 v[158:161], v220 offset:49152
	v_add_f32_e32 v163, v163, v60
	v_add_f32_e32 v162, v162, v61
	v_add_f32_e32 v163, v163, v62
	v_cvt_pk_bf16_f32 v130, v58, v59
	v_cvt_pk_bf16_f32 v131, v60, v61
	s_waitcnt lgkmcnt(4)
	v_mfma_f32_32x32x16_bf16 v[18:33], v[142:145], v[110:113], v[18:33]
	ds_read_b128 v[224:227], v220 offset:51200
	v_cvt_pk_bf16_f32 v132, v62, v63
	v_cvt_pk_bf16_f32 v133, v64, v65
	v_add_f32_e32 v162, v162, v63
	v_add_f32_e32 v163, v163, v64
	v_add_f32_e32 v162, v162, v65
	s_waitcnt lgkmcnt(4)
	v_mfma_f32_32x32x16_bf16 v[66:81], v[146:149], v[130:133], v[66:81]
	ds_read_b128 v[228:231], v140 offset:36864
	v_exp_f32_e32 v34, v34
	v_exp_f32_e32 v35, v35
	v_exp_f32_e32 v36, v36
	s_waitcnt lgkmcnt(4)
	v_mfma_f32_32x32x16_bf16 v[82:97], v[150:153], v[130:133], v[82:97]
	ds_read_b128 v[232:235], v140 offset:37376
	v_exp_f32_e32 v37, v37
	v_exp_f32_e32 v38, v38
	v_exp_f32_e32 v39, v39
	s_waitcnt lgkmcnt(4)
	v_mfma_f32_32x32x16_bf16 v[18:33], v[154:157], v[106:109], v[18:33]
	ds_read_b128 v[142:145], v220 offset:41472
	v_exp_f32_e32 v40, v40
	v_exp_f32_e32 v41, v41
	v_add_f32_e32 v163, v163, v34
	v_add_f32_e32 v162, v162, v35
	s_waitcnt lgkmcnt(4)
	v_mfma_f32_32x32x16_bf16 v[18:33], v[158:161], v[102:105], v[18:33]
	ds_read_b128 v[146:149], v220 offset:43520
	v_add_f32_e32 v163, v163, v36
	v_add_f32_e32 v162, v162, v37
	v_add_f32_e32 v163, v163, v38
	v_cvt_pk_bf16_f32 v134, v34, v35
	v_cvt_pk_bf16_f32 v135, v36, v37
	s_waitcnt lgkmcnt(4)
	v_mfma_f32_32x32x16_bf16 v[18:33], v[224:227], v[98:101], v[18:33]
	ds_read_b128 v[150:153], v220 offset:45568
	v_cvt_pk_bf16_f32 v136, v38, v39
	v_cvt_pk_bf16_f32 v137, v40, v41
	v_add_f32_e32 v162, v162, v39
	v_add_f32_e32 v163, v163, v40
	v_add_f32_e32 v162, v162, v41
	s_waitcnt lgkmcnt(4)
	v_mfma_f32_32x32x16_bf16 v[66:81], v[228:231], v[134:137], v[66:81]
	ds_read_b128 v[154:157], v140 offset:38912
	v_exp_f32_e32 v42, v42
	v_exp_f32_e32 v43, v43
	v_exp_f32_e32 v44, v44
	s_waitcnt lgkmcnt(4)
	v_mfma_f32_32x32x16_bf16 v[82:97], v[232:235], v[134:137], v[82:97]
	ds_read_b128 v[158:161], v140 offset:39424
	v_exp_f32_e32 v45, v45
	v_exp_f32_e32 v46, v46
	v_exp_f32_e32 v47, v47
	s_waitcnt lgkmcnt(4)
	v_mfma_f32_32x32x16_bf16 v[2:17], v[142:145], v[118:121], 0
	ds_read_b128 v[224:227], v220 offset:47616
	v_exp_f32_e32 v48, v48
	v_exp_f32_e32 v49, v49
	v_add_f32_e32 v163, v163, v42
	v_add_f32_e32 v162, v162, v43
	s_waitcnt lgkmcnt(4)
	v_mfma_f32_32x32x16_bf16 v[2:17], v[146:149], v[114:117], v[2:17]
	ds_read_b128 v[228:231], v220 offset:49664
	v_add_f32_e32 v163, v163, v44
	v_add_f32_e32 v162, v162, v45
	v_add_f32_e32 v163, v163, v46
	v_cvt_pk_bf16_f32 v130, v42, v43
	v_cvt_pk_bf16_f32 v131, v44, v45
	s_waitcnt lgkmcnt(4)
	v_mfma_f32_32x32x16_bf16 v[2:17], v[150:153], v[110:113], v[2:17]
	ds_read_b128 v[232:235], v220 offset:51712
	v_cvt_pk_bf16_f32 v132, v46, v47
	v_cvt_pk_bf16_f32 v133, v48, v49
	v_add_f32_e32 v162, v162, v47
	v_add_f32_e32 v163, v163, v48
	v_add_f32_e32 v162, v162, v49
	s_waitcnt lgkmcnt(4)
	v_mfma_f32_32x32x16_bf16 v[66:81], v[154:157], v[130:133], v[66:81]
	s_waitcnt lgkmcnt(3)
	v_mfma_f32_32x32x16_bf16 v[82:97], v[158:161], v[130:133], v[82:97]
	s_waitcnt lgkmcnt(2)
	v_mfma_f32_32x32x16_bf16 v[2:17], v[224:227], v[106:109], v[2:17]
	s_waitcnt lgkmcnt(1)
	v_mfma_f32_32x32x16_bf16 v[2:17], v[228:231], v[102:105], v[2:17]
	s_waitcnt lgkmcnt(0)
	v_mfma_f32_32x32x16_bf16 v[2:17], v[232:235], v[98:101], v[2:17]
	v_add_f32_e32 v138, v138, v163
	s_nop 0
	v_add_f32_e32 v138, v138, v162
	s_add_i32 s48, s48, 2
	s_add_i32 s9, s51, 2
	s_add_u32 s29, s29, 0x4000
	s_addc_u32 s30, s30, 0
	s_add_u32 s31, s31, 0x6000
	s_addc_u32 s33, s33, 0
	s_add_i32 s49, s49, 2
	s_add_i32 s50, s50, 0xa000
	s_branch .LBB0_503
